# static s_setprio 1 for waves 4-7 across the latent- and differential-attention tile loops (per-cluster priority flips in the diff QK section removed)
# speedup vs baseline: 1.0029x; 1.0029x over previous
; __device__ __forceinline__ unsigned cvt_pk_bf16(float lo, float hi) { const f32x2_ v = {lo, hi}; return __builtin_bit_cast(unsigned, __builtin_convertvector(v, bf16x2_)); }
; __device__ __forceinline__ float bf_lo(unsigned u) { return __uint_as_float(u << 16); }
; __device__ __forceinline__ float bf_hi(unsigned u) { return __uint_as_float(u & 0xffff0000u); }
; #define M2_LOAD(t) do { const size_t _tb = (size_t)M2_ROW(t); rk0 = *(const u32x4*)(Kp + (_tb + kr0) * ldk + kc0 * 8); \
;         if (hask1) rk1 = *(const u32x4*)(Kp + (_tb + kr1) * ldk + kc1 * 8); rv = *(const u32x4*)(Vp + (_tb + vr) * ldv + vc * 8); } while (0)
; #define M2_STORE(buf) do { LAS unsigned char* _kb = lds + (buf) * BUFSZ; *(LAS u32x4*)(_kb + kr0 * KSTR + kc0 * 16) = rk0; \
;         if (hask1) *(LAS u32x4*)(_kb + kr1 * KSTR + kc1 * 16) = rk1; *(LAS u32x4*)(_kb + KBUF + vr * VSTR + vc * 16) = rv; } while (0)
; __device__ __forceinline__ void attn_item_mla2(PK p, int l, LAS unsigned char* lds, int b, int h, int qb, bool ctxq) {
;     ...
;     const size_t qrow = (size_t)qrow0 + 32 * w + l32;
;     bf16x8 qf[NKS];
; #pragma unroll
;     for (int i = 0; i < NKS; ++i) {
;         const u32x4 raw = *(const u32x4*)(Qp + qrow * ldq + 16 * i + 8 * g);
;         u32x4 sc4; sc4.x = cvt_pk_bf16(bf_lo(raw.x) * cs, bf_hi(raw.x) * cs); sc4.y = cvt_pk_bf16(bf_lo(raw.y) * cs, bf_hi(raw.y) * cs);
;         sc4.z = cvt_pk_bf16(bf_lo(raw.z) * cs, bf_hi(raw.z) * cs); sc4.w = cvt_pk_bf16(bf_lo(raw.w) * cs, bf_hi(raw.w) * cs);
;         qf[i] = __builtin_bit_cast(bf16x8, sc4);
;     }
;     const int kr0 = tid / KCH, kc0 = tid % KCH, kr1 = (tid + 512) / KCH, kc1 = (tid + 512) % KCH, vr = tid >> 3, vc = tid & 7;
;     const bool hask1 = tid < 256;
;     u32x4 rk0, rk1 = (u32x4){0u, 0u, 0u, 0u}, rv;
;     ...
;     const int koff = l32 * KSTR + g * 16;
;     const int i16 = lane & 15, tq = i16 >> 2, tp = i16 & 3, blk = (lane >> 4) & 1;
;     const int voff = (4 * g + tq) * VSTR + (16 * blk + 4 * tp) * 2;
;     ...
;     M2_LOAD(0); M2_STORE(0); M2_LOAD(1); M2_STORE(1); __syncthreads();
;     M2_QK(SA, 0);
.LBB0_73:
	s_or_b64 exec, exec, s[0:1]
	v_lshlrev_b32_e32 v28, 3, v2
	v_lshl_add_u64 v[2:3], v[76:77], 0, s[88:89]
	v_lshlrev_b64 v[2:3], 9, v[2:3]
	v_lshl_add_u64 v[2:3], s[6:7], 0, v[2:3]
	v_lshlrev_b32_e32 v28, 1, v28
	v_mov_b32_e32 v29, v0
	v_lshl_add_u64 v[2:3], v[2:3], 0, v[28:29]
	global_load_dwordx4 v[106:109], v[2:3], off
	s_waitcnt vmcnt(1)
	ds_write_b128 v1, v[102:105] offset:25600
	s_and_saveexec_b64 s[0:1], vcc
	s_xor_b64 s[0:1], exec, s[0:1]
	v_lshlrev_b32_e32 v30, 4, v37
	s_or_saveexec_b64 s[0:1], s[0:1]
	s_lshl_b32 s26, s25, 6
	s_xor_b64 exec, exec, s[0:1]
	v_add3_u32 v2, 0, v31, v30
	ds_write_b128 v2, v[98:101] offset:25600
	s_or_b64 exec, exec, s[0:1]
	v_lshlrev_b32_e32 v2, 16, v24
	v_and_b32_e32 v3, 0xffff0000, v24
	s_mov_b32 s0, 0x3e16c740
	v_pk_mul_f32 v[2:3], v[2:3], s[0:1] op_sel_hi:[1,0]
	s_waitcnt vmcnt(0)
	ds_write_b128 v165, v[106:109] offset:38912
	v_cvt_pk_bf16_f32 v110, v2, v3
	v_lshlrev_b32_e32 v2, 16, v25
	v_and_b32_e32 v3, 0xffff0000, v25
	v_pk_mul_f32 v[2:3], v[2:3], s[0:1] op_sel_hi:[1,0]
	s_waitcnt lgkmcnt(0)
	v_cvt_pk_bf16_f32 v111, v2, v3
	v_lshlrev_b32_e32 v2, 16, v26
	v_and_b32_e32 v3, 0xffff0000, v26
	v_pk_mul_f32 v[2:3], v[2:3], s[0:1] op_sel_hi:[1,0]
	s_barrier
	v_cvt_pk_bf16_f32 v112, v2, v3
	v_lshlrev_b32_e32 v2, 16, v27
	v_and_b32_e32 v3, 0xffff0000, v27
	v_pk_mul_f32 v[2:3], v[2:3], s[0:1] op_sel_hi:[1,0]
	s_nop 0
	v_cvt_pk_bf16_f32 v113, v2, v3
	v_lshlrev_b32_e32 v2, 16, v20
	v_and_b32_e32 v3, 0xffff0000, v20
	v_pk_mul_f32 v[2:3], v[2:3], s[0:1] op_sel_hi:[1,0]
	v_lshlrev_b32_e32 v166, 2, v79
	v_cvt_pk_bf16_f32 v114, v2, v3
	v_lshlrev_b32_e32 v2, 16, v21
	v_and_b32_e32 v3, 0xffff0000, v21
	v_pk_mul_f32 v[2:3], v[2:3], s[0:1] op_sel_hi:[1,0]
	s_mov_b32 s8, 0
	v_cvt_pk_bf16_f32 v115, v2, v3
	v_lshlrev_b32_e32 v2, 16, v22
	v_and_b32_e32 v3, 0xffff0000, v22
	v_pk_mul_f32 v[2:3], v[2:3], s[0:1] op_sel_hi:[1,0]
	s_mov_b32 s9, s8
	v_cvt_pk_bf16_f32 v116, v2, v3
	v_lshlrev_b32_e32 v2, 16, v23
	v_and_b32_e32 v3, 0xffff0000, v23
	v_pk_mul_f32 v[2:3], v[2:3], s[0:1] op_sel_hi:[1,0]
	s_mov_b32 s10, s8
	v_cvt_pk_bf16_f32 v117, v2, v3
	v_lshlrev_b32_e32 v2, 16, v16
	v_and_b32_e32 v3, 0xffff0000, v16
	v_pk_mul_f32 v[2:3], v[2:3], s[0:1] op_sel_hi:[1,0]
	s_mov_b32 s11, s8
	v_cvt_pk_bf16_f32 v118, v2, v3
	v_lshlrev_b32_e32 v2, 16, v17
	v_and_b32_e32 v3, 0xffff0000, v17
	v_pk_mul_f32 v[2:3], v[2:3], s[0:1] op_sel_hi:[1,0]
	s_mov_b32 s12, s8
	v_cvt_pk_bf16_f32 v119, v2, v3
	v_lshlrev_b32_e32 v2, 16, v18
	v_and_b32_e32 v3, 0xffff0000, v18
	v_pk_mul_f32 v[2:3], v[2:3], s[0:1] op_sel_hi:[1,0]
	s_mov_b32 s13, s8
	v_cvt_pk_bf16_f32 v120, v2, v3
	v_lshlrev_b32_e32 v2, 16, v19
	v_and_b32_e32 v3, 0xffff0000, v19
	v_pk_mul_f32 v[2:3], v[2:3], s[0:1] op_sel_hi:[1,0]
	s_mov_b32 s14, s8
	v_cvt_pk_bf16_f32 v121, v2, v3
	v_lshlrev_b32_e32 v2, 16, v12
	v_and_b32_e32 v3, 0xffff0000, v12
	v_mul_u32_u24_e32 v12, 0xd0, v38
	v_add3_u32 v167, 0, v36, v12
	ds_read_b128 v[16:19], v167
	v_pk_mul_f32 v[2:3], v[2:3], s[0:1] op_sel_hi:[1,0]
	s_mov_b32 s15, s8
	v_cvt_pk_bf16_f32 v122, v2, v3
	v_lshlrev_b32_e32 v2, 16, v13
	v_and_b32_e32 v3, 0xffff0000, v13
	v_pk_mul_f32 v[2:3], v[2:3], s[0:1] op_sel_hi:[1,0]
	s_mov_b32 s16, s8
	v_cvt_pk_bf16_f32 v123, v2, v3
	v_lshlrev_b32_e32 v2, 16, v14
	v_and_b32_e32 v3, 0xffff0000, v14
	v_pk_mul_f32 v[2:3], v[2:3], s[0:1] op_sel_hi:[1,0]
	s_mov_b32 s17, s8
	v_cvt_pk_bf16_f32 v124, v2, v3
	v_lshlrev_b32_e32 v2, 16, v15
	v_and_b32_e32 v3, 0xffff0000, v15
	ds_read_b128 v[12:15], v167 offset:32
	s_waitcnt lgkmcnt(1)
	v_mfma_f32_32x32x16_bf16 v[50:65], v[16:19], v[110:113], 0
	ds_read_b128 v[16:19], v167 offset:64
	v_mul_f32_e64 v2, v2, s0
	v_mul_f32_e64 v3, v3, s0
	s_mov_b32 s18, s8
	v_cvt_pk_bf16_f32 v125, v2, v3
	v_lshlrev_b32_e32 v2, 16, v8
	v_and_b32_e32 v3, 0xffff0000, v8
	v_pk_mul_f32 v[2:3], v[2:3], s[0:1] op_sel_hi:[1,0]
	s_waitcnt lgkmcnt(1)
	v_mfma_f32_32x32x16_bf16 v[50:65], v[12:15], v[114:117], v[50:65]
	ds_read_b128 v[12:15], v167 offset:96
	v_cvt_pk_bf16_f32 v126, v2, v3
	v_lshlrev_b32_e32 v2, 16, v9
	v_and_b32_e32 v3, 0xffff0000, v9
	v_mul_f32_e64 v2, v2, s0
	v_mul_f32_e64 v3, v3, s0
	s_mov_b32 s19, s8
	v_cvt_pk_bf16_f32 v127, v2, v3
	s_waitcnt lgkmcnt(1)
	v_mfma_f32_32x32x16_bf16 v[50:65], v[16:19], v[118:121], v[50:65]
	v_lshlrev_b32_e32 v2, 16, v10
	v_and_b32_e32 v3, 0xffff0000, v10
	v_mul_f32_e64 v2, v2, s0
	v_mul_f32_e64 v3, v3, s0
	s_mov_b32 s20, s8
	v_cvt_pk_bf16_f32 v128, v2, v3
	v_lshlrev_b32_e32 v2, 16, v11
	v_and_b32_e32 v3, 0xffff0000, v11
	ds_read_b128 v[8:11], v167 offset:128
	s_waitcnt lgkmcnt(1)
	v_mfma_f32_32x32x16_bf16 v[50:65], v[12:15], v[122:125], v[50:65]
	v_mul_f32_e64 v2, v2, s0
	v_mul_f32_e64 v3, v3, s0
	v_lshlrev_b32_e32 v12, 16, v6
	v_cvt_pk_bf16_f32 v129, v2, v3
	v_lshlrev_b32_e32 v2, 16, v4
	v_and_b32_e32 v3, 0xffff0000, v4
	v_pk_mul_f32 v[2:3], v[2:3], s[0:1] op_sel_hi:[1,0]
	v_and_b32_e32 v13, 0xffff0000, v6
	v_cvt_pk_bf16_f32 v130, v2, v3
	v_lshlrev_b32_e32 v2, 16, v5
	v_and_b32_e32 v3, 0xffff0000, v5
	v_pk_mul_f32 v[2:3], v[2:3], s[0:1] op_sel_hi:[1,0]
	v_lshlrev_b32_e32 v6, 16, v7
	v_cvt_pk_bf16_f32 v131, v2, v3
	ds_read_b128 v[2:5], v167 offset:160
	s_waitcnt lgkmcnt(1)
; #define M2_LOAD(t) do { const size_t _tb = (size_t)M2_ROW(t); rk0 = *(const u32x4*)(Kp + (_tb + kr0) * ldk + kc0 * 8); \
;         if (hask1) rk1 = *(const u32x4*)(Kp + (_tb + kr1) * ldk + kc1 * 8); rv = *(const u32x4*)(Vp + (_tb + vr) * ldv + vc * 8); } while (0)
; #define M2_STORE(buf) do { LAS unsigned char* _kb = lds + (buf) * BUFSZ; *(LAS u32x4*)(_kb + kr0 * KSTR + kc0 * 16) = rk0; \
;         if (hask1) *(LAS u32x4*)(_kb + kr1 * KSTR + kc1 * 16) = rk1; *(LAS u32x4*)(_kb + KBUF + vr * VSTR + vc * 16) = rv; } while (0)
; #define M2_MAX(SX, MX) do { float _mx = -1e30f; _Pragma("unroll") for (int kt = 0; kt < 2; ++kt) _Pragma("unroll") for (int r = 0; r < 16; r += 2) _mx = fmaxf(fmaxf(_mx, SX[kt][r]), SX[kt][r + 1]); \
;         MX = fmaxf(_mx, shflx(_mx, 32)); } while (0)
; __device__ __forceinline__ void attn_item_mla2(PK p, int l, LAS unsigned char* lds, int b, int h, int qb, bool ctxq) {
;     ...
;     float lsum = 0.f, mrun; f32x16 O[2];
; #pragma unroll
;     for (int dt = 0; dt < 2; ++dt)
; #pragma unroll
;         for (int r = 0; r < 16; ++r) O[dt][r] = 0.f;
;     bf16x8 Pold[2][2];
; #pragma unroll
;     for (int kt = 0; kt < 2; ++kt)
; #pragma unroll
;         for (int s2 = 0; s2 < 2; ++s2) Pold[kt][s2] = (bf16x8){0, 0, 0, 0, 0, 0, 0, 0};
;     f32x16 SA[2], SB[2];
;     M2_LOAD(0); M2_STORE(0); M2_LOAD(1); M2_STORE(1); __syncthreads();
;     M2_QK(SA, 0);
;     bool zref;
;     { float mx0; M2_MAX(SA, mx0); zref = !__any(!(fabsf(mx0) < 40.0f)); mrun = zref ? 0.0f : mx0; }
;     int pbuf = 0;
	v_mfma_f32_32x32x16_bf16 v[50:65], v[8:11], v[126:129], v[50:65]
	v_and_b32_e32 v7, 0xffff0000, v7
	v_mul_f32_e64 v8, v12, s0
	v_mul_f32_e64 v9, v13, s0
	v_mul_f32_e64 v6, v6, s0
	v_mul_f32_e64 v7, v7, s0
	v_cvt_pk_bf16_f32 v132, v8, v9
	v_cvt_pk_bf16_f32 v133, v6, v7
	v_lshrrev_b32_e32 v10, 2, v78
	v_and_b32_e32 v11, 16, v78
	s_waitcnt lgkmcnt(0)
	v_mfma_f32_32x32x16_bf16 v[50:65], v[2:5], v[130:133], v[50:65]
	ds_read_b128 v[2:5], v167 offset:6656
	ds_read_b128 v[6:9], v167 offset:6688
	s_mov_b32 s21, s8
	s_mov_b32 s22, s8
	s_mov_b32 s23, s8
	v_lshl_add_u64 v[22:23], v[74:75], 1, s[2:3]
	v_mov_b32_e32 v29, v0
	v_lshl_add_u64 v[20:21], s[6:7], 0, v[28:29]
	s_waitcnt lgkmcnt(1)
	v_mfma_f32_32x32x16_bf16 v[34:49], v[2:5], v[110:113], 0
	ds_read_b128 v[2:5], v167 offset:6720
	v_add_u32_e32 v27, 0, v31
	v_mov_b32_e32 v142, 0
	v_add_u32_e32 v169, v27, v30
	v_mov_b32_e32 v173, 0
	v_mov_b32_e32 v143, v142
	v_mov_b32_e32 v144, v142
	s_waitcnt lgkmcnt(1)
	v_mfma_f32_32x32x16_bf16 v[34:49], v[6:9], v[114:117], v[34:49]
	ds_read_b128 v[6:9], v167 offset:6752
	v_mov_b32_e32 v145, v142
	v_mov_b32_e32 v146, v142
	v_mov_b32_e32 v147, v142
	v_mov_b32_e32 v148, v142
	v_mov_b32_e32 v149, v142
	v_mov_b32_e32 v134, v142
	s_waitcnt lgkmcnt(1)
	v_mfma_f32_32x32x16_bf16 v[34:49], v[2:5], v[118:121], v[34:49]
	v_and_or_b32 v2, v10, 3, v166
	v_lshlrev_b32_e32 v3, 2, v78
	v_and_or_b32 v3, v3, 12, v11
	v_mul_u32_u24_e32 v2, 0xc0, v2
	v_lshl_or_b32 v26, v3, 1, v2
	ds_read_b128 v[2:5], v167 offset:6784
	v_add_u32_e32 v168, 0, v26
	s_waitcnt lgkmcnt(1)
	v_mfma_f32_32x32x16_bf16 v[34:49], v[6:9], v[122:125], v[34:49]
	ds_read_b128 v[6:9], v167 offset:6816
	v_mov_b32_e32 v135, v142
	v_mov_b32_e32 v136, v142
	v_mov_b32_e32 v137, v142
	v_mov_b32_e32 v138, v142
	v_mov_b32_e32 v139, v142
	v_mov_b32_e32 v140, v142
	s_waitcnt lgkmcnt(1)
	v_mfma_f32_32x32x16_bf16 v[34:49], v[2:5], v[126:129], v[34:49]
	v_max3_f32 v2, v50, s33, v51
	v_max3_f32 v2, v2, v52, v53
	v_max3_f32 v2, v2, v54, v55
	v_max3_f32 v2, v2, v56, v57
	v_max3_f32 v2, v2, v58, v59
	v_max3_f32 v2, v2, v60, v61
	v_max3_f32 v2, v2, v62, v63
	s_waitcnt lgkmcnt(0)
	v_mfma_f32_32x32x16_bf16 v[34:49], v[6:9], v[130:133], v[34:49]
	v_max3_f32 v2, v2, v64, v65
	v_mov_b32_e32 v141, v142
	s_nop 9
	v_max3_f32 v2, v2, v34, v35
	v_max3_f32 v2, v2, v36, v37
	v_max3_f32 v2, v2, v38, v39
	v_max3_f32 v2, v2, v40, v41
	v_max3_f32 v2, v2, v42, v43
	v_max3_f32 v2, v2, v44, v45
	v_max3_f32 v2, v2, v46, v47
	v_max3_f32 v18, v2, v48, v49
	v_mov_b32_e32 v2, v220
	s_nop 0
	v_lshlrev_b32_e32 v2, 2, v2
	v_xor_b32_e32 v2, 0x80, v2
	ds_bpermute_b32 v19, v2, v18
	v_mov_b64_e32 v[2:3], s[8:9]
	v_mov_b64_e32 v[4:5], s[10:11]
	v_mov_b64_e32 v[6:7], s[12:13]
	v_mov_b64_e32 v[8:9], s[14:15]
	s_waitcnt lgkmcnt(0)
	v_max_f32_e32 v19, v19, v19
	v_max_f32_e32 v18, v18, v19
	v_cmp_nlt_f32_e64 s[0:1], |v18|, s53
	s_cmp_eq_u64 s[0:1], 0
	v_mov_b64_e32 v[10:11], s[16:17]
	v_mov_b64_e32 v[12:13], s[18:19]
	v_mov_b64_e32 v[14:15], s[20:21]
	v_mov_b64_e32 v[16:17], s[22:23]
	s_cselect_b64 s[12:13], -1, 0
	s_or_b32 s88, s27, 0x8080
	v_cndmask_b32_e64 v164, v18, 0, s[12:13]
	v_lshl_add_u64 v[18:19], v[70:71], 1, s[2:3]
	v_lshl_add_u64 v[24:25], v[66:67], 0, s[88:89]
	s_movk_i32 s2, 0x300
	v_mad_u64_u32 v[152:153], s[0:1], v24, s2, v[18:19]
	v_mad_i32_i24 v153, v25, s2, v153
	v_lshl_add_u64 v[24:25], v[68:69], 0, s[88:89]
	v_mad_u64_u32 v[154:155], s[0:1], v24, s2, v[22:23]
	v_mad_i32_i24 v155, v25, s2, v155
	v_lshl_add_u64 v[24:25], v[76:77], 0, s[88:89]
	v_lshlrev_b64 v[24:25], 9, v[24:25]
	s_or_b32 s88, s27, 0x80c0
	v_lshl_add_u64 v[156:157], v[20:21], 0, v[24:25]
	v_lshl_add_u64 v[24:25], v[66:67], 0, s[88:89]
	v_mad_u64_u32 v[158:159], s[0:1], v24, s2, v[18:19]
	v_lshl_add_u64 v[18:19], v[68:69], 0, s[88:89]
	v_mad_u64_u32 v[160:161], s[0:1], v18, s2, v[22:23]
	v_mad_i32_i24 v161, v19, s2, v161
	v_lshl_add_u64 v[18:19], v[76:77], 0, s[88:89]
	v_lshlrev_b64 v[18:19], 9, v[18:19]
	v_readlane_b32 s0, v254, 46
	v_lshl_add_u64 v[162:163], v[20:21], 0, v[18:19]
	v_mad_i32_i24 v159, v25, s2, v159
	v_add_u32_e32 v18, s0, v80
	v_add_u32_e32 v19, s0, v31
	s_add_i32 s0, 0, 0x16000
	v_add_u32_e32 v20, s0, v81
	v_add_u32_e32 v170, v18, v73
	v_add_u32_e32 v171, v19, v30
	v_add_u32_e32 v172, v20, v72
	v_mov_b64_e32 v[32:33], v[16:17]
	s_mov_b64 s[2:3], -1
	v_mov_b64_e32 v[30:31], v[14:15]
	v_mov_b64_e32 v[28:29], v[12:13]
	v_mov_b64_e32 v[26:27], v[10:11]
	v_mov_b64_e32 v[24:25], v[8:9]
	v_mov_b64_e32 v[22:23], v[6:7]
	v_mov_b64_e32 v[20:21], v[4:5]
	v_mov_b64_e32 v[18:19], v[2:3]
	v_readfirstlane_b32 s98, v189
	s_lshr_b32 s98, s98, 8
	s_cmp_eq_u32 s98, 0
	s_cbranch_scc1 .Lmla_prio_done
	s_setprio 1
.Lmla_prio_done:
	s_branch .LBB0_80
.LBB0_78:
	s_or_b64 exec, exec, s[0:1]
	s_waitcnt vmcnt(0)
	ds_write_b128 v172, v[106:109]

; __device__ __forceinline__ unsigned cvt_pk_bf16(float lo, float hi) { const f32x2_ v = {lo, hi}; return __builtin_bit_cast(unsigned, __builtin_convertvector(v, bf16x2_)); }
; __device__ __forceinline__ void attn_item_mla2(PK p, int l, LAS unsigned char* lds, int b, int h, int qb, bool ctxq) {
;     ...
;     M2_PVOLD(pbuf);
;     const float lt = lsum + shflx(lsum, 32); const float inv = 1.0f / lt;
;     bf16_t* op = (bf16_t*)(ws + OFF_A) + qrow * 1024 + outoff;
; #pragma unroll
;     for (int dt = 0; dt < 2; ++dt)
; #pragma unroll
;         for (int rq = 0; rq < 4; ++rq) { const int dv = 32 * dt + 8 * rq + 4 * g;
;             u32x2 wv; wv.x = cvt_pk_bf16(O[dt][4 * rq] * inv, O[dt][4 * rq + 1] * inv); wv.y = cvt_pk_bf16(O[dt][4 * rq + 2] * inv, O[dt][4 * rq + 3] * inv);
;             *(u32x2*)(op + dv) = wv; }
;     __syncthreads();
.LBB0_220:
	s_setprio 0
	v_add_u32_e32 v1, 0x16000, v168
	ds_read_b64_tr_b16 v[34:35], v1
	ds_read_b64_tr_b16 v[36:37], v1 offset:1536
	ds_read_b64_tr_b16 v[38:39], v1 offset:64
	ds_read_b64_tr_b16 v[40:41], v1 offset:1600
	ds_read_b64_tr_b16 v[42:43], v1 offset:3072
	ds_read_b64_tr_b16 v[44:45], v1 offset:4608
	ds_read_b64_tr_b16 v[46:47], v1 offset:3136
	ds_read_b64_tr_b16 v[48:49], v1 offset:4672
	s_waitcnt lgkmcnt(6)
	v_mfma_f32_32x32x16_bf16 v[2:17], v[34:37], v[142:145], v[2:17]
	s_lshl_b32 s88, s26, 1
	s_waitcnt lgkmcnt(4)
	v_mfma_f32_32x32x16_bf16 v[18:33], v[38:41], v[142:145], v[18:33]
	s_waitcnt lgkmcnt(2)
	v_mfma_f32_32x32x16_bf16 v[2:17], v[42:45], v[146:149], v[2:17]
	s_waitcnt lgkmcnt(0)
	v_mfma_f32_32x32x16_bf16 v[18:33], v[46:49], v[146:149], v[18:33]
	ds_read_b64_tr_b16 v[34:35], v1 offset:6144
	ds_read_b64_tr_b16 v[36:37], v1 offset:7680
	ds_read_b64_tr_b16 v[38:39], v1 offset:6208
	ds_read_b64_tr_b16 v[40:41], v1 offset:7744
	ds_read_b64_tr_b16 v[42:43], v1 offset:9216
	ds_read_b64_tr_b16 v[44:45], v1 offset:10752
	ds_read_b64_tr_b16 v[46:47], v1 offset:9280
	ds_read_b64_tr_b16 v[48:49], v1 offset:10816
	v_mov_b32_e32 v1, v220
	s_nop 0
	v_lshlrev_b32_e32 v1, 2, v1
	v_xor_b32_e32 v1, 0x80, v1
	ds_bpermute_b32 v1, v1, v173
	s_waitcnt lgkmcnt(7)
	v_mfma_f32_32x32x16_bf16 v[2:17], v[34:37], v[134:137], v[2:17]
	s_waitcnt lgkmcnt(0)
	v_add_f32_e32 v1, v173, v1
	v_div_scale_f32 v34, s[0:1], v1, v1, 1.0
	v_rcp_f32_e32 v35, v34
	v_mfma_f32_32x32x16_bf16 v[2:17], v[42:45], v[138:141], v[2:17]
	v_readlane_b32 s0, v254, 56
	v_readlane_b32 s1, v254, 57
	v_fma_f32 v36, -v34, v35, 1.0
	v_fmac_f32_e32 v35, v36, v35
	v_div_scale_f32 v36, vcc, 1.0, v1, 1.0
	v_mul_f32_e32 v37, v36, v35
	v_mfma_f32_32x32x16_bf16 v[18:33], v[38:41], v[134:137], v[18:33]
	v_fma_f32 v38, -v34, v37, v36
	v_fmac_f32_e32 v37, v38, v35
	v_fma_f32 v34, -v34, v37, v36
	v_div_fmas_f32 v34, v34, v35, v37
	v_div_fixup_f32 v34, v34, v1, 1.0
	v_lshlrev_b64 v[36:37], 11, v[150:151]
	v_lshl_add_u64 v[36:37], s[0:1], 0, v[36:37]
	v_pk_mul_f32 v[2:3], v[2:3], v[34:35] op_sel_hi:[1,0]
	v_pk_mul_f32 v[4:5], v[4:5], v[34:35] op_sel_hi:[1,0]
	v_lshl_add_u64 v[36:37], v[36:37], 0, s[88:89]
	v_cvt_pk_bf16_f32 v2, v2, v3
	v_cvt_pk_bf16_f32 v3, v4, v5
	v_lshlrev_b32_e32 v4, 1, v166
	v_mov_b32_e32 v5, v0
	v_lshl_add_u64 v[4:5], v[36:37], 0, v[4:5]
	s_mov_b64 s[0:1], 0x36de600
	v_lshl_add_u64 v[36:37], v[4:5], 0, s[0:1]
	s_mov_b32 s0, 0x36de000
	v_mfma_f32_32x32x16_bf16 v[18:33], v[46:49], v[138:141], v[18:33]
	v_add_co_u32_e32 v4, vcc, s0, v4
	s_nop 1
	v_addc_co_u32_e32 v5, vcc, 0, v5, vcc
	global_store_dwordx2 v[4:5], v[2:3], off offset:1536
	v_mul_f32_e64 v2, v6, v34
	v_mul_f32_e64 v3, v7, v34
	v_pk_mul_f32 v[4:5], v[8:9], v[34:35] op_sel_hi:[1,0]
	v_cvt_pk_bf16_f32 v2, v2, v3
	v_cvt_pk_bf16_f32 v3, v4, v5
	global_store_dwordx2 v[36:37], v[2:3], off offset:16
	v_pk_mul_f32 v[2:3], v[10:11], v[34:35] op_sel_hi:[1,0]
	v_pk_mul_f32 v[4:5], v[12:13], v[34:35] op_sel_hi:[1,0]
	v_cvt_pk_bf16_f32 v2, v2, v3
	v_cvt_pk_bf16_f32 v3, v4, v5
	global_store_dwordx2 v[36:37], v[2:3], off offset:32
	v_pk_mul_f32 v[2:3], v[14:15], v[34:35] op_sel_hi:[1,0]
	v_pk_mul_f32 v[4:5], v[16:17], v[34:35] op_sel_hi:[1,0]
	v_cvt_pk_bf16_f32 v2, v2, v3
	v_cvt_pk_bf16_f32 v3, v4, v5
	global_store_dwordx2 v[36:37], v[2:3], off offset:48
	v_pk_mul_f32 v[2:3], v[18:19], v[34:35] op_sel_hi:[1,0]
	v_pk_mul_f32 v[4:5], v[20:21], v[34:35] op_sel_hi:[1,0]
	v_cvt_pk_bf16_f32 v2, v2, v3
	v_cvt_pk_bf16_f32 v3, v4, v5
	global_store_dwordx2 v[36:37], v[2:3], off offset:64
	v_pk_mul_f32 v[2:3], v[22:23], v[34:35] op_sel_hi:[1,0]
	v_pk_mul_f32 v[4:5], v[24:25], v[34:35] op_sel_hi:[1,0]
	v_cvt_pk_bf16_f32 v2, v2, v3
	v_cvt_pk_bf16_f32 v3, v4, v5
	global_store_dwordx2 v[36:37], v[2:3], off offset:80
	v_pk_mul_f32 v[2:3], v[26:27], v[34:35] op_sel_hi:[1,0]
	v_pk_mul_f32 v[4:5], v[28:29], v[34:35] op_sel_hi:[1,0]
	v_cvt_pk_bf16_f32 v2, v2, v3
	v_cvt_pk_bf16_f32 v3, v4, v5
	global_store_dwordx2 v[36:37], v[2:3], off offset:96
	v_pk_mul_f32 v[2:3], v[30:31], v[34:35] op_sel_hi:[1,0]
	v_pk_mul_f32 v[4:5], v[32:33], v[34:35] op_sel_hi:[1,0]
	v_cvt_pk_bf16_f32 v2, v2, v3
	v_cvt_pk_bf16_f32 v3, v4, v5
	global_store_dwordx2 v[36:37], v[2:3], off offset:112
	s_barrier
	s_cbranch_execz .LBB0_105
	s_branch .LBB0_128

; __device__ __forceinline__ unsigned cvt_pk_bf16(float lo, float hi) { const f32x2_ v = {lo, hi}; return __builtin_bit_cast(unsigned, __builtin_convertvector(v, bf16x2_)); }
; __device__ __forceinline__ float bf_lo(unsigned u) { return __uint_as_float(u << 16); }
; __device__ __forceinline__ float bf_hi(unsigned u) { return __uint_as_float(u & 0xffff0000u); }
; #define LOAD_TILE(t) do { const size_t _tb = (size_t)TILE_ROW(t); rk0 = *(const u32x4*)(Kp + (_tb + kr0) * ldk + kc0 * 8); \
;         if (hask1) rk1 = *(const u32x4*)(Kp + (_tb + kr1) * ldk + kc1 * 8); rv = *(const u32x4*)(Vp + (_tb + vr) * ldv + vc * 8); } while (0)
; template <int MODE>
; __device__ __forceinline__ void attn_item(PK p, int l, LAS unsigned char* lds, int b, int h, int qb, bool ctxq, float lam, float lam_init) {
;     ...
;     const size_t qrow = (size_t)qrow0 + 32 * w + l32;
;     bf16x8 qf[NCOMP * NKS];
; #pragma unroll
;     for (int i = 0; i < NCOMP * NKS; ++i) {
;         const u32x4 raw = *(const u32x4*)(Qp + qrow * ldq + 16 * i + 8 * g);
;         u32x4 sc4; sc4.x = cvt_pk_bf16(bf_lo(raw.x) * cs, bf_hi(raw.x) * cs); sc4.y = cvt_pk_bf16(bf_lo(raw.y) * cs, bf_hi(raw.y) * cs);
;         sc4.z = cvt_pk_bf16(bf_lo(raw.z) * cs, bf_hi(raw.z) * cs); sc4.w = cvt_pk_bf16(bf_lo(raw.w) * cs, bf_hi(raw.w) * cs);
;         qf[i] = __builtin_bit_cast(bf16x8, sc4);
;     }
;     const int kr0 = tid / KCH, kc0 = tid % KCH, kr1 = (tid + 512) / KCH, kc1 = (tid + 512) % KCH, vr = tid >> 3, vc = tid & 7;
;     const bool hask1 = (KCH == 12) && (tid < 256);
;     u32x4 rk0, rk1 = (u32x4){0u, 0u, 0u, 0u}, rv;
;     ...
;     float mrun[NCOMP], lsum[NCOMP]; f32x16 O[NCOMP][2];
; #pragma unroll
;     for (int c = 0; c < NCOMP; ++c) { mrun[c] = -1e30f; lsum[c] = 0.f;
; #pragma unroll
;         for (int dt = 0; dt < 2; ++dt)
; #pragma unroll
;             for (int r = 0; r < 16; ++r) O[c][dt][r] = 0.f; }
;     bf16x8 P[NCOMP][2][2];
; #pragma unroll
;     for (int c = 0; c < NCOMP; ++c)
; #pragma unroll
;         for (int kt = 0; kt < 2; ++kt)
; #pragma unroll
;             for (int s2 = 0; s2 < 2; ++s2) P[c][kt][s2] = (bf16x8){0, 0, 0, 0, 0, 0, 0, 0};
;     LOAD_TILE(0); STORE_TILE(0); __syncthreads();
.LBB0_264:
	s_lshl_b32 s16, s29, 6
	s_lshl_b32 s4, s29, 7
	v_readlane_b32 s0, v255, 19
	s_add_u32 s0, s0, s4
	v_readlane_b32 s1, v255, 20
	s_addc_u32 s1, s1, 0
	v_readlane_b32 s2, v255, 21
	s_add_u32 s2, s2, s4
	v_readlane_b32 s3, v255, 22
	v_mov_b32_e32 v1, v189
	s_addc_u32 s3, s3, 0
	v_readlane_b32 s5, v255, 23
	s_add_u32 s4, s5, s4
	v_readlane_b32 s5, v255, 24
	v_readlane_b32 s7, v255, 26
	v_ashrrev_i32_e32 v2, 1, v1
	v_and_b32_e32 v33, 31, v1
	s_addc_u32 s5, s5, 0
	s_lshl_b32 s6, s28, 13
	s_lshl_b32 s7, s7, 8
	v_and_b32_e32 v2, 0xffffffe0, v2
	s_or_b32 s88, s6, s7
	v_ashrrev_i32_e32 v3, 31, v2
	v_or_b32_e32 v2, v2, v33
	v_bfe_u32 v32, v1, 5, 1
	v_lshl_add_u64 v[200:201], v[2:3], 0, s[88:89]
	v_mov_b64_e32 v[2:3], s[0:1]
	v_mad_i64_i32 v[4:5], s[0:1], v200, s56, v[2:3]
	v_lshlrev_b32_e32 v2, 4, v32
	v_mov_b32_e32 v3, v0
	v_lshl_add_u64 v[16:17], v[4:5], 0, v[2:3]
	global_load_dwordx4 v[4:7], v[16:17], off
	global_load_dwordx4 v[8:11], v[16:17], off offset:32
	global_load_dwordx4 v[12:15], v[16:17], off offset:64
	v_ashrrev_i32_e32 v3, 31, v1
	global_load_dwordx4 v[16:19], v[16:17], off offset:96
	v_lshrrev_b32_e32 v3, 29, v3
	v_add_u32_e32 v3, v1, v3
	v_ashrrev_i32_e32 v208, 3, v3
	v_and_b32_e32 v3, -8, v3
	s_mov_b32 s7, s89
	v_lshlrev_b32_e32 v20, 4, v1
	v_sub_u32_e32 v3, v1, v3
	v_ashrrev_i32_e32 v209, 31, v208
	v_and_b32_e32 v204, 0x70, v20
	v_mov_b64_e32 v[20:21], s[2:3]
	v_lshl_add_u64 v[22:23], v[208:209], 0, s[6:7]
	v_lshlrev_b32_e32 v24, 3, v3
	v_mad_u64_u32 v[20:21], s[0:1], v22, s56, v[20:21]
	v_ashrrev_i32_e32 v25, 31, v24
	v_ashrrev_i32_e32 v206, 3, v1
	v_mad_i32_i24 v21, v23, s56, v21
	v_lshlrev_b64 v[22:23], 1, v[24:25]
	v_add_u32_e32 v28, s6, v206
	v_mov_b64_e32 v[26:27], s[4:5]
	v_lshl_add_u64 v[20:21], v[20:21], 0, v[22:23]
	v_mov_b32_e32 v205, v0
	global_load_dwordx4 v[132:135], v[20:21], off
	v_mad_i64_i32 v[20:21], s[0:1], v28, s56, v[26:27]
	v_lshl_add_u64 v[20:21], v[20:21], 0, v[204:205]
	global_load_dwordx4 v[136:139], v[20:21], off
	s_mov_b32 s0, 0x3e8293ee
	v_lshlrev_b32_e32 v234, 4, v3
	v_lshlrev_b32_e32 v232, 2, v32
	v_mov_b32_e32 v142, v0
	v_mov_b32_e32 v143, v0
	s_lshl_b32 s7, s28, 8
	v_lshl_add_u64 v[210:211], s[2:3], 0, v[22:23]
	v_mov_b32_e32 v140, v0
	v_mov_b32_e32 v141, v0
	v_mov_b64_e32 v[166:167], v[142:143]
	v_mov_b64_e32 v[182:183], v[142:143]
	v_mov_b64_e32 v[186:187], v[142:143]
	v_mov_b64_e32 v[154:155], v[142:143]
	v_mov_b64_e32 v[146:147], v[142:143]
	v_mov_b64_e32 v[174:175], v[142:143]
	v_mov_b64_e32 v[178:179], v[142:143]
	s_bitset1_b32 s7, 15
	v_ashrrev_i32_e32 v207, 31, v206
	v_lshl_add_u64 v[212:213], s[4:5], 0, v[204:205]
	s_mov_b32 s19, 0
	s_mov_b64 s[2:3], 0
	v_mov_b32_e32 v240, 0xf149f2ca
	v_mov_b64_e32 v[164:165], v[140:141]
	v_mov_b64_e32 v[180:181], v[140:141]
	v_mov_b64_e32 v[184:185], v[140:141]
	v_mov_b64_e32 v[152:153], v[140:141]
	v_mov_b64_e32 v[144:145], v[140:141]
	v_mov_b64_e32 v[172:173], v[140:141]
	v_mov_b64_e32 v[176:177], v[140:141]
	v_mov_b32_e32 v238, 0xf149f2ca
	s_mov_b32 s17, 0
	s_waitcnt vmcnt(5)
	v_lshlrev_b32_e32 v20, 16, v4
	v_and_b32_e32 v21, 0xffff0000, v4
	v_lshlrev_b32_e32 v4, 16, v5
	v_and_b32_e32 v5, 0xffff0000, v5
	s_waitcnt vmcnt(3)
	v_lshlrev_b32_e32 v30, 16, v12
	v_and_b32_e32 v31, 0xffff0000, v12
	v_pk_mul_f32 v[4:5], v[4:5], s[0:1] op_sel_hi:[1,0]
	v_lshlrev_b32_e32 v24, 16, v6
	v_cvt_pk_bf16_f32 v149, v4, v5
	v_pk_mul_f32 v[4:5], v[30:31], s[0:1] op_sel_hi:[1,0]
	v_and_b32_e32 v25, 0xffff0000, v6
	v_cvt_pk_bf16_f32 v160, v4, v5
	v_lshlrev_b32_e32 v4, 16, v13
	v_and_b32_e32 v5, 0xffff0000, v13
	v_pk_mul_f32 v[4:5], v[4:5], s[0:1] op_sel_hi:[1,0]
	v_lshlrev_b32_e32 v6, 16, v7
	v_cvt_pk_bf16_f32 v161, v4, v5
	v_lshlrev_b32_e32 v4, 16, v14
	v_and_b32_e32 v5, 0xffff0000, v14
	v_pk_mul_f32 v[4:5], v[4:5], s[0:1] op_sel_hi:[1,0]
	v_and_b32_e32 v7, 0xffff0000, v7
	v_cvt_pk_bf16_f32 v162, v4, v5
	v_lshlrev_b32_e32 v4, 16, v15
	v_and_b32_e32 v5, 0xffff0000, v15
	v_pk_mul_f32 v[4:5], v[4:5], s[0:1] op_sel_hi:[1,0]
	v_lshlrev_b32_e32 v26, 16, v8
	v_cvt_pk_bf16_f32 v163, v4, v5
	s_waitcnt vmcnt(2)
; #define LAS __attribute__((address_space(3)))
; __device__ __forceinline__ float bf_lo(unsigned u) { return __uint_as_float(u << 16); }
; template <int MODE>
; __device__ __forceinline__ void attn_item(PK p, int l, LAS unsigned char* lds, int b, int h, int qb, bool ctxq, float lam, float lam_init) {
;     ...
;     bf16x8 qf[NCOMP * NKS];
; #pragma unroll
;     for (int i = 0; i < NCOMP * NKS; ++i) {
;         const u32x4 raw = *(const u32x4*)(Qp + qrow * ldq + 16 * i + 8 * g);
;         u32x4 sc4; sc4.x = cvt_pk_bf16(bf_lo(raw.x) * cs, bf_hi(raw.x) * cs); sc4.y = cvt_pk_bf16(bf_lo(raw.y) * cs, bf_hi(raw.y) * cs);
;         sc4.z = cvt_pk_bf16(bf_lo(raw.z) * cs, bf_hi(raw.z) * cs); sc4.w = cvt_pk_bf16(bf_lo(raw.w) * cs, bf_hi(raw.w) * cs);
;         qf[i] = __builtin_bit_cast(bf16x8, sc4);
;     }
;     const int kr0 = tid / KCH, kc0 = tid % KCH, kr1 = (tid + 512) / KCH, kc1 = (tid + 512) % KCH, vr = tid >> 3, vc = tid & 7;
;     const bool hask1 = (KCH == 12) && (tid < 256);
;     u32x4 rk0, rk1 = (u32x4){0u, 0u, 0u, 0u}, rv;
;     ...
;     float mrun[NCOMP], lsum[NCOMP]; f32x16 O[NCOMP][2];
; #pragma unroll
;     for (int c = 0; c < NCOMP; ++c) { mrun[c] = -1e30f; lsum[c] = 0.f;
; #pragma unroll
;         for (int dt = 0; dt < 2; ++dt)
; #pragma unroll
;             for (int r = 0; r < 16; ++r) O[c][dt][r] = 0.f; }
;     bf16x8 P[NCOMP][2][2];
; #pragma unroll
;     for (int c = 0; c < NCOMP; ++c)
; #pragma unroll
;         for (int kt = 0; kt < 2; ++kt)
; #pragma unroll
;             for (int s2 = 0; s2 < 2; ++s2) P[c][kt][s2] = (bf16x8){0, 0, 0, 0, 0, 0, 0, 0};
;     LOAD_TILE(0); STORE_TILE(0); __syncthreads();
;     ...
;     for (int t = 0; t < nt; ++t) {
;         const bool more = (t + 1 < nt);
;         if (more) LOAD_TILE(t + 1);
;         bool active = true; int krow = 0;
;         if (nabias && t < nloc) { krow = loc0 + t; active = (krow >= sw) && (krow < sw + 8); }
;         bool slow = (MODE == 0) || (t == 0);
;         if (active) {
;           again:
;             LAS unsigned char* Kb = lds + cbuf * BUFSZ + koff;
;             f32x16 S[NCOMP][2];
; #pragma unroll
;             for (int c = 0; c < NCOMP; ++c)
; #pragma unroll
;                 for (int kt = 0; kt < 2; ++kt) {
;                     bf16x8 kf[NKS];
; #pragma unroll
;                     for (int ks = 0; ks < NKS; ++ks) kf[ks] = *(const LAS bf16x8*)(Kb + kt * 32 * KSTR + (c * NKS + ks) * 32);
	v_lshlrev_b32_e32 v4, 16, v16
	v_and_b32_e32 v5, 0xffff0000, v16
	v_pk_mul_f32 v[4:5], v[4:5], s[0:1] op_sel_hi:[1,0]
	v_and_b32_e32 v27, 0xffff0000, v8
	v_cvt_pk_bf16_f32 v168, v4, v5
	v_lshlrev_b32_e32 v4, 16, v17
	v_and_b32_e32 v5, 0xffff0000, v17
	v_pk_mul_f32 v[4:5], v[4:5], s[0:1] op_sel_hi:[1,0]
	v_lshlrev_b32_e32 v8, 16, v9
	v_cvt_pk_bf16_f32 v169, v4, v5
	v_lshlrev_b32_e32 v4, 16, v18
	v_and_b32_e32 v5, 0xffff0000, v18
	v_pk_mul_f32 v[4:5], v[4:5], s[0:1] op_sel_hi:[1,0]
	v_and_b32_e32 v9, 0xffff0000, v9
	v_lshlrev_b32_e32 v28, 16, v10
	v_and_b32_e32 v29, 0xffff0000, v10
	v_lshlrev_b32_e32 v10, 16, v11
	v_and_b32_e32 v11, 0xffff0000, v11
	v_cvt_pk_bf16_f32 v170, v4, v5
	v_lshlrev_b32_e32 v4, 16, v19
	v_and_b32_e32 v5, 0xffff0000, v19
	v_pk_mul_f32 v[20:21], v[20:21], s[0:1] op_sel_hi:[1,0]
	v_pk_mul_f32 v[24:25], v[24:25], s[0:1] op_sel_hi:[1,0]
	v_pk_mul_f32 v[6:7], v[6:7], s[0:1] op_sel_hi:[1,0]
	v_pk_mul_f32 v[26:27], v[26:27], s[0:1] op_sel_hi:[1,0]
	v_pk_mul_f32 v[8:9], v[8:9], s[0:1] op_sel_hi:[1,0]
	v_pk_mul_f32 v[28:29], v[28:29], s[0:1] op_sel_hi:[1,0]
	v_pk_mul_f32 v[10:11], v[10:11], s[0:1] op_sel_hi:[1,0]
	v_pk_mul_f32 v[4:5], v[4:5], s[0:1] op_sel_hi:[1,0]
	s_movk_i32 s0, 0x90
	v_cvt_pk_bf16_f32 v171, v4, v5
	v_mul_lo_u32 v233, v208, s0
	s_movk_i32 s0, 0xc0
	v_lshrrev_b32_e32 v4, 2, v1
	v_add3_u32 v3, 0, v233, v234
	v_mul_lo_u32 v235, v206, s0
	v_and_b32_e32 v5, 16, v1
	v_and_or_b32 v4, v4, 3, v232
	v_lshlrev_b32_e32 v1, 2, v1
	s_waitcnt vmcnt(1)
	ds_write_b128 v3, v[132:135]
	v_add3_u32 v3, 0, v235, v204
	v_and_or_b32 v1, v1, 12, v5
	v_mul_u32_u24_e32 v4, 0xc0, v4
	v_mov_b32_e32 v18, v0
	v_mov_b32_e32 v19, v0
	v_cvt_pk_bf16_f32 v148, v20, v21
	v_cvt_pk_bf16_f32 v150, v24, v25
	v_cvt_pk_bf16_f32 v151, v6, v7
	v_cvt_pk_bf16_f32 v156, v26, v27
	v_cvt_pk_bf16_f32 v157, v8, v9
	v_cvt_pk_bf16_f32 v158, v28, v29
	v_cvt_pk_bf16_f32 v159, v10, v11
	s_waitcnt vmcnt(0)
	ds_write_b128 v3, v[136:139] offset:9216
	v_mul_u32_u24_e32 v3, 0x90, v33
	v_lshl_or_b32 v236, v1, 1, v4
	v_mov_b32_e32 v1, v0
	v_mov_b32_e32 v4, v0
	v_mov_b32_e32 v5, v0
	v_mov_b32_e32 v6, v0
	v_mov_b32_e32 v7, v0
	v_mov_b32_e32 v8, v0
	v_mov_b32_e32 v9, v0
	v_mov_b32_e32 v10, v0
	v_mov_b32_e32 v11, v0
	v_mov_b32_e32 v12, v0
	v_mov_b32_e32 v13, v0
	v_mov_b32_e32 v14, v0
	v_mov_b32_e32 v15, v0
	v_mov_b32_e32 v16, v0
	v_mov_b32_e32 v17, v0
	v_mov_b64_e32 v[50:51], v[18:19]
	v_mov_b64_e32 v[34:35], v[18:19]
	v_mov_b64_e32 v[66:67], v[18:19]
	v_add3_u32 v205, 0, v3, v2
	v_add_u32_e32 v237, 0, v236
	v_mov_b64_e32 v[48:49], v[16:17]
	v_mov_b64_e32 v[46:47], v[14:15]
	v_mov_b64_e32 v[44:45], v[12:13]
	v_mov_b64_e32 v[42:43], v[10:11]
	v_mov_b64_e32 v[40:41], v[8:9]
	v_mov_b64_e32 v[38:39], v[6:7]
	v_mov_b64_e32 v[36:37], v[4:5]
	v_mov_b64_e32 v[32:33], v[16:17]
	v_mov_b64_e32 v[30:31], v[14:15]
	v_mov_b64_e32 v[28:29], v[12:13]
	v_mov_b64_e32 v[26:27], v[10:11]
	v_mov_b64_e32 v[24:25], v[8:9]
	v_mov_b64_e32 v[22:23], v[6:7]
	v_mov_b64_e32 v[20:21], v[4:5]
	v_mov_b64_e32 v[64:65], v[16:17]
	v_mov_b64_e32 v[62:63], v[14:15]
	v_mov_b64_e32 v[60:61], v[12:13]
	v_mov_b64_e32 v[58:59], v[10:11]
	v_mov_b64_e32 v[56:57], v[8:9]
	v_mov_b64_e32 v[54:55], v[6:7]
	v_mov_b64_e32 v[52:53], v[4:5]
	s_mov_b32 s0, 0
	v_mov_b64_e32 v[202:203], v[0:1]
	s_waitcnt lgkmcnt(0)
	s_barrier
	v_readfirstlane_b32 s98, v189
	s_lshr_b32 s98, s98, 8
	s_cmp_eq_u32 s98, 0
	s_cbranch_scc1 .Ldiff_prio_done
	s_setprio 1
.Ldiff_prio_done:
.LBB0_265:
	s_add_i32 s18, s0, 1
	s_cmpk_lt_u32 s0, 0x83
	s_cselect_b64 s[8:9], -1, 0
	s_cmp_eq_u32 s0, 0
	s_cselect_b64 s[10:11], -1, 0
	s_mov_b64 s[12:13], s[10:11]
	s_mul_i32 s1, s17, 0x5400
	v_add_u32_e32 v239, s1, v205
	ds_read_b128 v[72:75], v239
	ds_read_b128 v[76:79], v239 offset:32
	ds_read_b128 v[80:83], v239 offset:4608
	ds_read_b128 v[222:225], v239 offset:4640
	ds_read_b128 v[226:229], v239 offset:64
	ds_read_b128 v[246:249], v239 offset:96
	ds_read_b128 v[68:71], v239 offset:4672
	ds_read_b128 v[190:193], v239 offset:4704
	s_cmpk_gt_u32 s0, 0x82
	s_cbranch_scc1 .Ldiff_mfma
	s_cmpk_lt_u32 s0, 0x7f
	s_cselect_b32 s1, 0, 0xffffff80
	s_cselect_b32 s4, s6, s7
	s_add_i32 s1, s1, s18
	s_lshl_b32 s1, s1, 6
	s_add_i32 s88, s1, s4
	v_lshl_add_u64 v[2:3], s[88:89], 0, v[208:209]
	v_mad_u64_u32 v[250:251], s[4:5], v2, s56, v[210:211]
	v_mad_i32_i24 v251, v3, s56, v251
	v_lshl_add_u64 v[2:3], s[88:89], 0, v[206:207]
	v_mad_u64_u32 v[252:253], s[4:5], v2, s56, v[212:213]
	v_mad_i32_i24 v253, v3, s56, v253
	global_load_dwordx4 v[132:135], v[250:251], off
	global_load_dwordx4 v[136:139], v[252:253], off
	s_branch .Ldiff_mfma

; template <int MODE>
; __device__ __forceinline__ void attn_item(PK p, int l, LAS unsigned char* lds, int b, int h, int qb, bool ctxq, float lam, float lam_init) {
;     ...
; #pragma unroll
;             for (int c = 0; c < NCOMP; ++c)
; #pragma unroll
;                 for (int kt = 0; kt < 2; ++kt) {
;                     bf16x8 kf[NKS];
; #pragma unroll
;                     for (int ks = 0; ks < NKS; ++ks) kf[ks] = *(const LAS bf16x8*)(Kb + kt * 32 * KSTR + (c * NKS + ks) * 32);
; #pragma unroll
;                     for (int r = 0; r < 16; ++r) S[c][kt][r] = 0.f;
;                     __builtin_amdgcn_s_setprio(1);
; #pragma unroll
;                     for (int ks = 0; ks < NKS; ++ks) S[c][kt] = MFMA32(kf[ks], qf[c * NKS + ks], S[c][kt]);
;                     __builtin_amdgcn_s_setprio(0);
;                 }
;             if (STAG && late && pend) { PV_TILE(pbuf); pend = false; }
;             float mxc[NCOMP], mnw[NCOMP];
;             if (!slow) {
; #pragma unroll
;                 for (int c = 0; c < NCOMP; ++c) mnw[c] = mrun[c];
;             } else {
; #pragma unroll
;             for (int c = 0; c < NCOMP; ++c) {
;                 float mx = -1e30f;
;                 if (nabias && t < nloc) {
;                     const LAS float* bt = (const LAS float*)(lds + BIAS_OFF) + (krow - rw + 7) * 31;
; #pragma unroll
;                     for (int kt = 0; kt < 2; ++kt)
; #pragma unroll
;                         for (int r = 0; r < 16; ++r) { const int jk = 32 * kt + (r & 3) + 8 * (r >> 2) + 4 * g; const bool ok = (jk >= cst) && (jk < cst + 16);
;                             const float bv = bt[clampi(jk - jq + 15, 0, 30)]; const float xv = ok ? (S[c][kt][r] + bv) : -1e30f; S[c][kt][r] = xv; mx = fmaxf(mx, xv); }
;                 } else {
; #pragma unroll
;                     for (int kt = 0; kt < 2; ++kt)
; #pragma unroll
;                         for (int r = 0; r < 16; r += 2) mx = fmaxf(fmaxf(mx, S[c][kt][r]), S[c][kt][r + 1]);
;                 }
;                 mxc[c] = mx;
;             }
; #pragma unroll
;             for (int c = 0; c < NCOMP; ++c) mxc[c] = fmaxf(mxc[c], shflx(mxc[c], 32));
;             bool grow = false;
; #pragma unroll
;             for (int c = 0; c < NCOMP; ++c) { mnw[c] = fmaxf(mrun[c], mxc[c]); grow = grow || (mnw[c] > mrun[c]); }
;             if (MODE != 0) {
;                 bool big = false;
; #pragma unroll
.Ldiff_mfma:
	s_xor_b64 s[14:15], s[12:13], -1
	s_waitcnt lgkmcnt(7)
	v_mfma_f32_32x32x16_bf16 v[116:131], v[72:75], v[148:151], 0
	s_waitcnt lgkmcnt(6)
	v_mfma_f32_32x32x16_bf16 v[116:131], v[76:79], v[156:159], v[116:131]
	s_waitcnt lgkmcnt(5)
	v_mfma_f32_32x32x16_bf16 v[100:115], v[80:83], v[148:151], 0
	s_waitcnt lgkmcnt(4)
	v_mfma_f32_32x32x16_bf16 v[100:115], v[222:225], v[156:159], v[100:115]
	s_waitcnt lgkmcnt(3)
	v_mfma_f32_32x32x16_bf16 v[84:99], v[226:229], v[160:163], 0
	s_waitcnt lgkmcnt(2)
	v_mfma_f32_32x32x16_bf16 v[84:99], v[246:249], v[168:171], v[84:99]
	s_waitcnt lgkmcnt(1)
	v_mfma_f32_32x32x16_bf16 v[68:83], v[68:71], v[160:163], 0
	s_waitcnt lgkmcnt(0)
	v_mfma_f32_32x32x16_bf16 v[68:83], v[190:193], v[168:171], v[68:83]
	s_and_b64 vcc, exec, s[14:15]
	s_cbranch_vccnz .LBB0_281
	s_nop 0
	v_max3_f32 v2, v84, s33, v85
	v_max3_f32 v2, v2, v86, v87
	v_max3_f32 v2, v2, v88, v89
	v_max3_f32 v1, v116, s33, v117
	v_max3_f32 v2, v2, v90, v91
	v_max3_f32 v1, v1, v118, v119
	v_max3_f32 v2, v2, v92, v93
	v_max3_f32 v1, v1, v120, v121
	v_max3_f32 v2, v2, v94, v95
	v_max3_f32 v1, v1, v122, v123
	v_max3_f32 v2, v2, v96, v97
	v_max3_f32 v1, v1, v124, v125
	v_max3_f32 v2, v2, v98, v99
	v_max3_f32 v1, v1, v126, v127
	v_max3_f32 v2, v2, v68, v69
	v_max3_f32 v1, v1, v128, v129
	v_max3_f32 v2, v2, v70, v71
	v_max3_f32 v1, v1, v130, v131
	v_max3_f32 v2, v2, v72, v73
	v_max3_f32 v1, v1, v100, v101
	v_max3_f32 v2, v2, v74, v75
	v_max3_f32 v1, v1, v102, v103
	v_max3_f32 v2, v2, v76, v77
	v_max3_f32 v1, v1, v104, v105
	v_max3_f32 v2, v2, v78, v79
	v_max3_f32 v1, v1, v106, v107
	v_max3_f32 v2, v2, v80, v81
	v_max3_f32 v1, v1, v108, v109
	v_max3_f32 v3, v2, v82, v83
	v_mov_b32_e32 v2, v220
	v_mov_b32_e32 v190, v220
	v_max3_f32 v1, v1, v110, v111
	v_max3_f32 v1, v1, v112, v113
	v_lshlrev_b32_e32 v2, 2, v2
	v_lshlrev_b32_e32 v190, 2, v190
	v_max3_f32 v1, v1, v114, v115
	v_xor_b32_e32 v2, 0x80, v2
	v_xor_b32_e32 v190, 0x80, v190
	ds_bpermute_b32 v2, v2, v1
	ds_bpermute_b32 v190, v190, v3
	s_andn2_b64 vcc, exec, s[10:11]
	s_mov_b64 s[2:3], 0
	s_waitcnt lgkmcnt(1)
	v_max3_f32 v2, v240, v1, v2
	s_waitcnt lgkmcnt(0)
	v_max3_f32 v1, v238, v3, v190
	s_cbranch_vccnz .LBB0_272
	v_cmp_nlt_f32_e64 s[0:1], |v2|, s53
	v_cmp_nlt_f32_e64 s[2:3], |v1|, s53
	s_or_b64 s[0:1], s[0:1], s[2:3]
	v_cndmask_b32_e64 v3, 0, 1, s[0:1]
	v_cmp_ne_u32_e32 vcc, 0, v3
	s_cmp_eq_u64 vcc, 0
	s_cselect_b64 s[2:3], -1, 0

; #define STORE_TILE(buf) do { LAS unsigned char* _kb = lds + (buf) * BUFSZ; *(LAS u32x4*)(_kb + kr0 * KSTR + kc0 * 16) = rk0; \
;         if (hask1) *(LAS u32x4*)(_kb + kr1 * KSTR + kc1 * 16) = rk1; *(LAS u32x4*)(_kb + KBUF + vr * VSTR + vc * 16) = rv; } while (0)
; template <int MODE>
; __device__ __forceinline__ void attn_item(PK p, int l, LAS unsigned char* lds, int b, int h, int qb, bool ctxq, float lam, float lam_init) {
;     ...
;         const int nbuf = (cbuf == 2) ? 0 : cbuf + 1;
;         if (more) STORE_TILE(nbuf);
;         __syncthreads();
;         cbuf = nbuf;
;     }
.LBB0_284:
	s_cmpk_lg_i32 s18, 0x84
	s_waitcnt lgkmcnt(0)
	s_barrier
	s_cbranch_scc1 .Ldiff_cont
	s_setprio 0
	s_branch .LBB0_54
.Ldiff_cont:
	s_mov_b32 s0, s18
	s_branch .LBB0_265
